# diff-attn K/V LDS ring 2->3 stages, DMA prefetch distance 2 with counted vmcnt (on v_m11)
# baseline (speedup 1.0000x reference)
.LBB0_44:
	s_cmpk_gt_i32 s54, 0x7ff
	s_cbranch_scc1 .LBB0_43
	s_waitcnt vmcnt(10)
	v_mov_b32_e32 v54, v224
	s_ashr_i32 s55, s54, 5
	v_readfirstlane_b32 s0, v54
	s_sub_i32 s57, 63, s55
	s_ashr_i32 s0, s0, 1
	s_lshl_b32 s1, s57, 7
	s_and_b32 s52, s0, 0xffffffe0
	s_add_i32 s52, s52, s1
	s_bfe_u32 s56, s54, 0x10004
	s_and_b32 s48, s54, 15
	v_and_or_b32 v170, v54, 15, s52
	s_lshl_b32 s94, s56, 13
	s_lshl_b32 s0, s48, 7
	v_ashrrev_i32_e32 v171, 31, v170
	s_add_u32 s0, s13, s0
	v_lshl_add_u64 v[172:173], v[170:171], 0, s[94:95]
	s_addc_u32 s1, s14, 0
	v_and_b32_e32 v0, 16, v54
	v_lshlrev_b64 v[2:3], 11, v[172:173]
	v_cmp_eq_u32_e64 s[40:41], 0, v0
	s_waitcnt vmcnt(1)
	v_lshl_add_u64 v[14:15], s[0:1], 0, v[2:3]
	v_and_b32_e32 v0, 48, v54
	v_lshl_add_u64 v[6:7], v[14:15], 0, v[0:1]
	v_lshlrev_b64 v[10:11], 6, v[170:171]
	global_load_dwordx4 v[2:5], v[6:7], off offset:64
	s_nop 0
	global_load_dwordx4 v[6:9], v[6:7], off
	v_lshl_add_u64 v[22:23], s[4:5], 0, v[10:11]
	global_load_dwordx4 v[10:13], v[14:15], off
	s_nop 0
	global_load_dwordx4 v[14:17], v[14:15], off offset:16
	v_or_b32_e32 v176, 16, v170
	v_and_b32_e32 v55, 63, v54
	v_ashrrev_i32_e32 v177, 31, v176
	v_cmp_gt_u32_e32 vcc, 32, v55
	v_lshl_add_u64 v[174:175], v[176:177], 0, s[94:95]
	v_mov_b32_e32 v90, v1
	v_mov_b32_e32 v91, v1
	v_mov_b32_e32 v92, v1
	v_mov_b32_e32 v93, v1
	v_lshlrev_b32_e32 v193, 4, v54
	v_lshlrev_b32_e32 v197, 4, v55
	v_mov_b64_e32 v[70:71], v[90:91]
	v_mov_b64_e32 v[104:105], v[92:93]
	v_mov_b64_e32 v[66:67], v[90:91]
	v_mov_b64_e32 v[100:101], v[92:93]
	v_mov_b64_e32 v[58:59], v[90:91]
	v_mov_b64_e32 v[96:97], v[92:93]
	v_mov_b64_e32 v[86:87], v[90:91]
	v_mov_b64_e32 v[82:83], v[90:91]
	v_mov_b64_e32 v[78:79], v[90:91]
	v_mov_b64_e32 v[74:75], v[90:91]
	s_mov_b32 s49, 63
	s_mov_b32 s53, 0
	v_mov_b32_e32 v200, 0xf149f2ca
	v_mov_b32_e32 v198, 0xf149f2ca
	v_mov_b64_e32 v[72:73], v[92:93]
	v_mov_b64_e32 v[102:103], v[90:91]
	v_mov_b64_e32 v[68:69], v[92:93]
	v_mov_b64_e32 v[98:99], v[90:91]
	v_mov_b64_e32 v[60:61], v[92:93]
	v_mov_b64_e32 v[94:95], v[90:91]
	v_mov_b64_e32 v[88:89], v[92:93]
	v_mov_b64_e32 v[84:85], v[92:93]
	v_mov_b64_e32 v[80:81], v[92:93]
	v_mov_b64_e32 v[76:77], v[92:93]
	s_waitcnt vmcnt(1)
	v_lshlrev_b32_e32 v26, 16, v10
	s_waitcnt vmcnt(0)
	v_lshlrev_b32_e32 v27, 16, v14
	v_and_b32_e32 v29, 0xffff0000, v14
	v_and_b32_e32 v28, 0xffff0000, v10
	v_lshlrev_b32_e32 v31, 16, v15
	v_lshlrev_b32_e32 v30, 16, v11
	v_and_b32_e32 v33, 0xffff0000, v15
	v_and_b32_e32 v32, 0xffff0000, v11
	v_lshlrev_b32_e32 v35, 16, v16
	v_lshlrev_b32_e32 v34, 16, v12
	v_and_b32_e32 v37, 0xffff0000, v16
	v_and_b32_e32 v36, 0xffff0000, v12
	v_lshlrev_b32_e32 v39, 16, v17
	v_lshlrev_b32_e32 v38, 16, v13
	v_and_b32_e32 v41, 0xffff0000, v17
	v_and_b32_e32 v40, 0xffff0000, v13
	global_load_dwordx4 v[10:13], v[22:23], off offset:48
	global_load_dwordx4 v[14:17], v[22:23], off offset:16
	global_load_dwordx4 v[18:21], v[22:23], off offset:32
	s_nop 0
	global_load_dwordx4 v[22:25], v[22:23], off
	s_waitcnt vmcnt(1)
	v_mov_b32_e32 v43, v18
	s_waitcnt vmcnt(0)
	v_mov_b32_e32 v42, v22
	v_pk_mul_f32 v[42:43], v[42:43], v[26:27]
	s_nop 0
	v_sub_f32_e32 v44, v42, v43
	v_mov_b32_e32 v42, v18
	v_mov_b32_e32 v43, v22
	v_pk_mul_f32 v[26:27], v[42:43], v[26:27]
	v_mov_b32_e32 v22, v19
	v_add_f32_e32 v18, v26, v27
	v_cndmask_b32_e64 v42, v18, v44, s[40:41]
	v_mov_b32_e32 v18, v23
	v_pk_mul_f32 v[26:27], v[18:19], v[28:29]
	v_pk_mul_f32 v[18:19], v[22:23], v[28:29]
	v_sub_f32_e32 v26, v26, v27
	v_add_f32_e32 v18, v19, v18
	v_cndmask_b32_e64 v22, v18, v26, s[40:41]
	v_mov_b32_e32 v18, v24
	v_mov_b32_e32 v19, v20
	v_pk_mul_f32 v[18:19], v[18:19], v[30:31]
	s_nop 0
	v_sub_f32_e32 v23, v18, v19
	v_mov_b32_e32 v18, v20
	v_mov_b32_e32 v19, v24
	v_pk_mul_f32 v[18:19], v[18:19], v[30:31]
	v_mov_b32_e32 v20, v25
	v_add_f32_e32 v18, v19, v18
	v_cndmask_b32_e64 v23, v18, v23, s[40:41]
	v_pk_mul_f32 v[18:19], v[20:21], v[32:33]
	v_mov_b32_e32 v24, v21
	v_sub_f32_e32 v20, v18, v19
	v_pk_mul_f32 v[18:19], v[24:25], v[32:33]
	s_nop 0
	v_add_f32_e32 v18, v19, v18
	v_cndmask_b32_e64 v20, v18, v20, s[40:41]
	v_mov_b32_e32 v18, v14
	v_mov_b32_e32 v19, v10
	v_pk_mul_f32 v[18:19], v[18:19], v[34:35]
	s_nop 0
	v_sub_f32_e32 v21, v18, v19
	v_mov_b32_e32 v18, v10
	v_mov_b32_e32 v19, v14
	v_pk_mul_f32 v[18:19], v[18:19], v[34:35]
	v_mov_b32_e32 v14, v11
	v_add_f32_e32 v10, v19, v18
	v_cndmask_b32_e64 v21, v10, v21, s[40:41]
	v_mov_b32_e32 v10, v15
	v_pk_mul_f32 v[18:19], v[10:11], v[36:37]
	v_pk_mul_f32 v[10:11], v[14:15], v[36:37]
	v_sub_f32_e32 v18, v18, v19
	v_add_f32_e32 v10, v11, v10
	v_cndmask_b32_e64 v14, v10, v18, s[40:41]
	v_mov_b32_e32 v10, v16
	v_mov_b32_e32 v11, v12
	v_pk_mul_f32 v[10:11], v[10:11], v[38:39]
	v_lshlrev_b64 v[18:19], 6, v[176:177]
	v_sub_f32_e32 v15, v10, v11
	v_mov_b32_e32 v10, v12
	v_mov_b32_e32 v11, v16
	v_pk_mul_f32 v[10:11], v[10:11], v[38:39]
	v_mov_b32_e32 v12, v17
	v_add_f32_e32 v10, v11, v10
	v_cndmask_b32_e64 v15, v10, v15, s[40:41]
	v_pk_mul_f32 v[10:11], v[12:13], v[40:41]
	v_mov_b32_e32 v16, v13
	v_sub_f32_e32 v12, v10, v11
	v_pk_mul_f32 v[10:11], v[16:17], v[40:41]
	v_cvt_pk_bf16_f32 v13, v21, v14
	v_add_f32_e32 v10, v11, v10
	v_cndmask_b32_e64 v10, v10, v12, s[40:41]
	v_cvt_pk_bf16_f32 v11, v42, v22
	v_cvt_pk_bf16_f32 v10, v15, v10
	v_cndmask_b32_e32 v9, v9, v10, vcc
	v_cndmask_b32_e32 v6, v6, v11, vcc
	v_lshlrev_b64 v[10:11], 11, v[174:175]
	v_cvt_pk_bf16_f32 v12, v23, v20
	v_lshl_add_u64 v[22:23], s[0:1], 0, v[10:11]
	v_lshl_add_u64 v[14:15], v[22:23], 0, v[0:1]
	v_cndmask_b32_e32 v8, v8, v13, vcc
	v_cndmask_b32_e32 v7, v7, v12, vcc
	global_load_dwordx4 v[10:13], v[14:15], off offset:64
	s_nop 0
	global_load_dwordx4 v[14:17], v[14:15], off
	v_lshl_add_u64 v[30:31], s[4:5], 0, v[18:19]
	global_load_dwordx4 v[18:21], v[22:23], off
	s_nop 0
	global_load_dwordx4 v[22:25], v[22:23], off offset:16
	s_waitcnt vmcnt(1)
	v_lshlrev_b32_e32 v48, 16, v18
	s_waitcnt vmcnt(0)
	v_lshlrev_b32_e32 v49, 16, v22
	v_and_b32_e32 v47, 0xffff0000, v22
	v_and_b32_e32 v46, 0xffff0000, v18
	v_lshlrev_b32_e32 v45, 16, v23
	v_lshlrev_b32_e32 v44, 16, v19
	v_and_b32_e32 v43, 0xffff0000, v23
	v_and_b32_e32 v42, 0xffff0000, v19
	v_lshlrev_b32_e32 v41, 16, v24
	v_lshlrev_b32_e32 v40, 16, v20
	v_and_b32_e32 v39, 0xffff0000, v24
	v_and_b32_e32 v38, 0xffff0000, v20
	v_lshlrev_b32_e32 v37, 16, v25
	v_lshlrev_b32_e32 v36, 16, v21
	v_and_b32_e32 v35, 0xffff0000, v25
	v_and_b32_e32 v34, 0xffff0000, v21
	global_load_dwordx4 v[18:21], v[30:31], off offset:48
	global_load_dwordx4 v[22:25], v[30:31], off offset:16
	global_load_dwordx4 v[26:29], v[30:31], off offset:32
	s_nop 0
	global_load_dwordx4 v[30:33], v[30:31], off
	s_barrier
	s_waitcnt vmcnt(1)
	v_mov_b32_e32 v51, v26
	s_waitcnt vmcnt(0)
	v_mov_b32_e32 v50, v30
	v_pk_mul_f32 v[50:51], v[50:51], v[48:49]
	s_nop 0
	v_sub_f32_e32 v0, v50, v51
	v_mov_b32_e32 v50, v26
	v_mov_b32_e32 v51, v30
	v_pk_mul_f32 v[48:49], v[50:51], v[48:49]
	v_mov_b32_e32 v30, v27
	v_add_f32_e32 v26, v48, v49
	v_cndmask_b32_e64 v0, v26, v0, s[40:41]
	v_mov_b32_e32 v26, v31
	v_pk_mul_f32 v[48:49], v[26:27], v[46:47]
	v_pk_mul_f32 v[26:27], v[30:31], v[46:47]
	v_sub_f32_e32 v48, v48, v49
	v_add_f32_e32 v26, v27, v26
	v_cndmask_b32_e64 v30, v26, v48, s[40:41]
	v_mov_b32_e32 v26, v32
	v_mov_b32_e32 v27, v28
	v_pk_mul_f32 v[26:27], v[26:27], v[44:45]
	v_cvt_pk_bf16_f32 v0, v0, v30
	v_sub_f32_e32 v31, v26, v27
	v_mov_b32_e32 v26, v28
	v_mov_b32_e32 v27, v32
	v_pk_mul_f32 v[26:27], v[26:27], v[44:45]
	v_mov_b32_e32 v28, v33
	v_add_f32_e32 v26, v27, v26
	v_cndmask_b32_e64 v31, v26, v31, s[40:41]
	v_pk_mul_f32 v[26:27], v[28:29], v[42:43]
	v_mov_b32_e32 v32, v29
	v_sub_f32_e32 v28, v26, v27
	v_pk_mul_f32 v[26:27], v[32:33], v[42:43]
	v_cndmask_b32_e32 v14, v14, v0, vcc
	v_add_f32_e32 v26, v27, v26
	v_cndmask_b32_e64 v28, v26, v28, s[40:41]
	v_mov_b32_e32 v26, v22
	v_mov_b32_e32 v27, v18
	v_pk_mul_f32 v[26:27], v[26:27], v[40:41]
	v_mov_b64_e32 v[46:47], v[90:91]
	v_sub_f32_e32 v29, v26, v27
	v_mov_b32_e32 v26, v18
	v_mov_b32_e32 v27, v22
	v_pk_mul_f32 v[26:27], v[26:27], v[40:41]
	v_mov_b32_e32 v22, v19
	v_add_f32_e32 v18, v27, v26
	v_cndmask_b32_e64 v29, v18, v29, s[40:41]
	v_mov_b32_e32 v18, v23
	v_pk_mul_f32 v[26:27], v[18:19], v[38:39]
	v_pk_mul_f32 v[18:19], v[22:23], v[38:39]
	v_sub_f32_e32 v26, v26, v27
	v_add_f32_e32 v18, v19, v18
	v_cndmask_b32_e64 v22, v18, v26, s[40:41]
	v_mov_b32_e32 v18, v24
	v_mov_b32_e32 v19, v20
	v_pk_mul_f32 v[18:19], v[18:19], v[36:37]
	v_lshlrev_b32_e32 v26, 3, v54
	v_sub_f32_e32 v23, v18, v19
	v_mov_b32_e32 v18, v20
	v_mov_b32_e32 v19, v24
	v_pk_mul_f32 v[18:19], v[18:19], v[36:37]
	v_mov_b32_e32 v20, v25
	v_add_f32_e32 v18, v19, v18
	v_cndmask_b32_e64 v23, v18, v23, s[40:41]
	v_pk_mul_f32 v[18:19], v[20:21], v[34:35]
	v_mov_b32_e32 v24, v21
	v_sub_f32_e32 v20, v18, v19
	v_pk_mul_f32 v[18:19], v[24:25], v[34:35]
	v_ashrrev_i32_e32 v27, 31, v26
	v_add_f32_e32 v18, v19, v18
	v_cndmask_b32_e64 v18, v18, v20, s[40:41]
	s_lshl_b32 s40, s54, 20
	v_cvt_pk_bf16_f32 v20, v29, v22
	s_and_b32 s0, s40, 0x1f00000
	v_add_u32_e32 v22, 0x800, v26
	v_cvt_pk_bf16_f32 v18, v23, v18
	s_add_u32 s0, s15, s0
	v_ashrrev_i32_e32 v23, 31, v22
	v_cvt_pk_bf16_f32 v19, v31, v28
	s_addc_u32 s1, s44, 0
	v_lshlrev_b64 v[28:29], 1, v[26:27]
	v_lshlrev_b64 v[34:35], 1, v[22:23]
	v_cndmask_b32_e32 v17, v17, v18, vcc
	v_cndmask_b32_e32 v15, v15, v19, vcc
	v_lshl_add_u64 v[18:19], s[0:1], 0, v[28:29]
	v_lshl_add_u64 v[22:23], s[0:1], 0, v[34:35]
	s_and_b32 s0, s40, 0xe00000
	s_lshl_b32 s1, s56, 24
	s_lshl_b32 s41, s57, 1
	s_or_b32 s40, s1, s0
	s_add_u32 s0, s45, s40
	s_addc_u32 s1, s46, 0
	v_lshl_add_u64 v[30:31], s[0:1], 0, v[28:29]
	v_lshl_add_u64 v[36:37], s[0:1], 0, v[34:35]
	global_load_dwordx4 v[30:33], v[30:31], off
	v_cndmask_b32_e32 v16, v16, v20, vcc
	global_load_dwordx4 v[42:45], v[36:37], off
	v_add_u32_e32 v36, 0x1000, v26
	v_ashrrev_i32_e32 v37, 31, v36
	v_add_u32_e32 v26, 0x1800, v26
	v_lshlrev_b64 v[36:37], 1, v[36:37]
	v_ashrrev_i32_e32 v27, 31, v26
	v_lshl_add_u64 v[38:39], s[0:1], 0, v[36:37]
	v_lshlrev_b64 v[26:27], 1, v[26:27]
	global_load_dwordx4 v[50:53], v[38:39], off
	v_lshl_add_u64 v[38:39], s[0:1], 0, v[26:27]
	global_load_dwordx4 v[18:21], v[18:19], off
	s_add_i32 s0, s41, 2
	global_load_dwordx4 v[22:25], v[22:23], off
	v_readlane_b32 s1, v254, 13
	global_load_dwordx4 v[62:65], v[38:39], off
	s_add_u32 s40, s1, s40
	v_readlane_b32 s1, v254, 14
	v_cmp_lt_i32_e32 vcc, v247, v214
	s_addc_u32 s41, s1, 0
	s_and_b32 s1, s54, 31
	v_cndmask_b32_e32 v0, v225, v247, vcc
	v_cmp_lt_i32_e32 vcc, v246, v214
	v_mov_b32_e32 v180, v34
	v_mov_b32_e32 v181, v28
	v_mov_b32_e32 v182, v36
	s_mov_b64 s[98:99], s[40:41]
	v_mov_b32_e32 v184, v26
	s_lshl_b32 s1, s1, 20
	v_readlane_b32 s40, v254, 15
	v_lshlrev_b32_e32 v177, 2, v0
	v_cndmask_b32_e32 v0, v225, v246, vcc
	s_add_u32 s40, s40, s1
	v_readlane_b32 s1, v254, 16
	v_lshlrev_b32_e32 v171, 2, v0
	v_lshrrev_b32_e32 v0, 2, v54
	s_addc_u32 s41, s1, 0
	v_and_b32_e32 v192, 12, v0
	s_mov_b64 s[2:3], s[40:41]
	v_readfirstlane_b32 s41, v193
	s_add_u32 m0, s41, 0x6000
	s_nop 0
	global_load_lds_dwordx4 v181, s[2:3]
	s_add_u32 m0, m0, 0x1000
	s_nop 0
	global_load_lds_dwordx4 v180, s[2:3]
	s_add_u32 m0, m0, 0x1000
	s_nop 0
	global_load_lds_dwordx4 v181, s[98:99]
	s_add_u32 m0, m0, 0x1000
	s_nop 0
	global_load_lds_dwordx4 v180, s[98:99]
	s_add_u32 m0, m0, 0x1000
	s_nop 0
	global_load_lds_dwordx4 v182, s[98:99]
	s_add_u32 m0, m0, 0x1000
	s_nop 0
	global_load_lds_dwordx4 v184, s[98:99]
	s_add_u32 s98, s98, 0x4000
	s_addc_u32 s99, s99, 0
	s_add_u32 s2, s2, 0x2000
	s_addc_u32 s3, s3, 0
	s_lshl_b32 s1, s55, 1
	v_mov_b32_e32 v0, v1
	v_mov_b64_e32 v[54:55], v[90:91]
	v_mov_b64_e32 v[38:39], v[90:91]
	v_mov_b64_e32 v[34:35], v[90:91]
	v_mov_b64_e32 v[26:27], v[90:91]
	s_sub_i32 s1, 0, s1
	s_movk_i32 s54, 0xff80
	v_mov_b64_e32 v[56:57], v[92:93]
	v_mov_b64_e32 v[48:49], v[92:93]
	v_mov_b64_e32 v[40:41], v[92:93]
	v_mov_b64_e32 v[36:37], v[92:93]
	v_mov_b64_e32 v[28:29], v[92:93]
	v_mov_b64_e32 v[178:179], v[0:1]
	s_waitcnt vmcnt(6)
	ds_write_b128 v193, v[18:21]
	ds_write_b128 v193, v[22:25] offset:4096
	ds_write_b128 v193, v[30:33] offset:8192
	ds_write_b128 v193, v[42:45] offset:12288
	ds_write_b128 v193, v[50:53] offset:16384
	ds_write_b128 v193, v[62:65] offset:20480
.LBB0_46:
	s_mul_i32 s40, s53, 0x6000
	s_add_i32 s41, s54, 0x81
	s_cmp_ge_u32 s41, s0
	s_cbranch_scc1 .Lmy_d3w0
	s_waitcnt vmcnt(6)
	s_branch .Lmy_d3wd

.Lmy_d3wd:
	s_waitcnt lgkmcnt(0)
	s_barrier
	s_add_i32 s41, s54, 0x82
	s_cmp_ge_u32 s41, s0
	s_cbranch_scc1 .LBB0_48
	s_sub_i32 vcc_lo, s53, 1
	s_cmp_eq_u32 s53, 0
	s_cselect_b32 vcc_lo, 2, vcc_lo
	s_mul_i32 vcc_lo, vcc_lo, 0x6000
	v_readfirstlane_b32 s41, v193
	s_add_u32 m0, vcc_lo, s41
	s_nop 0
	global_load_lds_dwordx4 v181, s[2:3]
	s_add_u32 m0, m0, 0x1000
	s_nop 0
	global_load_lds_dwordx4 v180, s[2:3]
	s_add_u32 m0, m0, 0x1000
	s_nop 0
	global_load_lds_dwordx4 v181, s[98:99]
	s_add_u32 m0, m0, 0x1000
	s_nop 0
	global_load_lds_dwordx4 v180, s[98:99]
	s_add_u32 m0, m0, 0x1000
	s_nop 0
	global_load_lds_dwordx4 v182, s[98:99]
	s_add_u32 m0, m0, 0x1000
	s_nop 0
	global_load_lds_dwordx4 v184, s[98:99]

.LBB0_52:
	v_mul_f32_e32 v195, 0xbe38aa3b, v199
	v_fmamk_f32 v167, v167, 0x3e38aa3b, v195
	v_exp_f32_e32 v194, v167
	v_fmamk_f32 v167, v168, 0x3e38aa3b, v195
	v_fmamk_f32 v163, v163, 0x3e38aa3b, v195
	v_fmamk_f32 v159, v159, 0x3e38aa3b, v195
	v_mul_f32_e32 v196, 0xbe38aa3b, v201
	v_fmamk_f32 v166, v166, 0x3e38aa3b, v195
	v_exp_f32_e32 v168, v167
	v_fmamk_f32 v167, v169, 0x3e38aa3b, v195
	v_exp_f32_e32 v204, v163
	v_fmamk_f32 v163, v164, 0x3e38aa3b, v195
	v_exp_f32_e32 v208, v159
	v_fmamk_f32 v159, v160, 0x3e38aa3b, v195
	v_fmamk_f32 v155, v155, 0x3e38aa3b, v195
	v_fmamk_f32 v150, v150, 0x3e38aa3b, v196
	v_exp_f32_e32 v166, v166
	v_exp_f32_e32 v202, v167
	v_fmamk_f32 v162, v162, 0x3e38aa3b, v195
	v_exp_f32_e32 v164, v163
	v_fmamk_f32 v163, v165, 0x3e38aa3b, v195
	v_fmamk_f32 v158, v158, 0x3e38aa3b, v195
	v_exp_f32_e32 v160, v159
	v_fmamk_f32 v159, v161, 0x3e38aa3b, v195
	v_fmamk_f32 v154, v154, 0x3e38aa3b, v195
	v_exp_f32_e32 v212, v155
	v_fmamk_f32 v155, v156, 0x3e38aa3b, v195
	v_fmac_f32_e32 v195, 0x3e38aa3b, v157
	v_exp_f32_e32 v167, v150
	v_fmamk_f32 v150, v151, 0x3e38aa3b, v196
	v_exp_f32_e32 v216, v195
	v_exp_f32_e32 v195, v150
	v_fmamk_f32 v150, v152, 0x3e38aa3b, v196
	v_exp_f32_e32 v169, v150
	v_fmamk_f32 v150, v153, 0x3e38aa3b, v196
	v_exp_f32_e32 v203, v150
	v_fmamk_f32 v146, v146, 0x3e38aa3b, v196
	v_exp_f32_e32 v162, v162
	v_exp_f32_e32 v206, v163
	v_exp_f32_e32 v163, v146
	v_fmamk_f32 v146, v147, 0x3e38aa3b, v196
	v_pk_add_f32 v[150:151], v[166:167], 0 op_sel_hi:[1,0]
	v_exp_f32_e32 v205, v146
	v_fmamk_f32 v146, v148, 0x3e38aa3b, v196
	v_pk_add_f32 v[150:151], v[194:195], v[150:151]
	v_exp_f32_e32 v165, v146
	v_fmamk_f32 v146, v149, 0x3e38aa3b, v196
	v_pk_add_f32 v[150:151], v[168:169], v[150:151]
	v_exp_f32_e32 v207, v146
	v_pk_add_f32 v[150:151], v[202:203], v[150:151]
	v_fmamk_f32 v142, v142, 0x3e38aa3b, v196
	v_exp_f32_e32 v158, v158
	v_exp_f32_e32 v210, v159
	v_pk_add_f32 v[150:151], v[162:163], v[150:151]
	v_exp_f32_e32 v159, v142
	v_fmamk_f32 v142, v143, 0x3e38aa3b, v196
	v_pk_add_f32 v[150:151], v[204:205], v[150:151]
	v_exp_f32_e32 v209, v142
	v_fmamk_f32 v142, v144, 0x3e38aa3b, v196
	v_fmamk_f32 v138, v138, 0x3e38aa3b, v196
	v_exp_f32_e32 v156, v155
	v_pk_add_f32 v[150:151], v[164:165], v[150:151]
	v_exp_f32_e32 v161, v142
	v_fmamk_f32 v142, v145, 0x3e38aa3b, v196
	v_exp_f32_e32 v155, v138
	v_fmamk_f32 v138, v139, 0x3e38aa3b, v196
	v_pk_add_f32 v[150:151], v[206:207], v[150:151]
	v_exp_f32_e32 v211, v142
	v_exp_f32_e32 v213, v138
	v_fmamk_f32 v138, v140, 0x3e38aa3b, v196
	v_exp_f32_e32 v154, v154
	v_exp_f32_e32 v157, v138
	v_pk_add_f32 v[138:139], v[158:159], v[150:151]
	v_fmac_f32_e32 v196, 0x3e38aa3b, v141
	v_pk_add_f32 v[138:139], v[208:209], v[138:139]
	v_exp_f32_e32 v217, v196
	v_pk_add_f32 v[138:139], v[160:161], v[138:139]
	v_cvt_pk_bf16_f32 v146, v166, v194
	v_pk_add_f32 v[138:139], v[210:211], v[138:139]
	v_cvt_pk_bf16_f32 v147, v168, v202
	v_pk_add_f32 v[138:139], v[154:155], v[138:139]
	v_cvt_pk_bf16_f32 v148, v162, v204
	v_pk_add_f32 v[138:139], v[212:213], v[138:139]
	v_cvt_pk_bf16_f32 v149, v164, v206
	v_pk_add_f32 v[138:139], v[156:157], v[138:139]
	v_cvt_pk_bf16_f32 v140, v154, v212
	v_pk_add_f32 v[142:143], v[216:217], v[138:139]
	v_cvt_pk_bf16_f32 v138, v158, v208
	v_cvt_pk_bf16_f32 v139, v160, v210
	v_cvt_pk_bf16_f32 v141, v156, v216
	v_pk_add_f32 v[178:179], v[142:143], v[178:179]
	v_cvt_pk_bf16_f32 v142, v167, v195
	v_cvt_pk_bf16_f32 v143, v169, v203
	v_cvt_pk_bf16_f32 v144, v163, v205
	v_cvt_pk_bf16_f32 v145, v165, v207
	v_cvt_pk_bf16_f32 v150, v159, v209
	v_cvt_pk_bf16_f32 v151, v161, v211
	v_cvt_pk_bf16_f32 v152, v155, v213
	v_cvt_pk_bf16_f32 v153, v157, v217
	ds_read_b128 v[154:157], v0 offset:16384
	ds_read_b128 v[158:161], v0 offset:17408
	ds_read_b128 v[162:165], v0 offset:18432
	ds_read_b128 v[166:169], v0 offset:19456
	ds_read_b128 v[202:205], v0 offset:20480
	ds_read_b128 v[206:209], v0 offset:21504
	ds_read_b128 v[210:213], v0 offset:22528
	ds_read_b128 v[216:219], v0 offset:23552
	s_waitcnt lgkmcnt(8)
	v_mfma_f32_16x16x32_bf16 v[90:93], v[134:137], v[146:149], v[90:93]
	v_mfma_f32_16x16x32_bf16 v[70:73], v[134:137], v[142:145], v[70:73]
	v_mfma_f32_16x16x32_bf16 v[102:105], v[126:129], v[146:149], v[102:105]
	v_mfma_f32_16x16x32_bf16 v[66:69], v[126:129], v[142:145], v[66:69]
	v_mfma_f32_16x16x32_bf16 v[98:101], v[118:121], v[146:149], v[98:101]
	v_mfma_f32_16x16x32_bf16 v[58:61], v[118:121], v[142:145], v[58:61]
	v_mfma_f32_16x16x32_bf16 v[94:97], v[110:113], v[146:149], v[94:97]
	v_mfma_f32_16x16x32_bf16 v[54:57], v[110:113], v[142:145], v[54:57]
	s_waitcnt lgkmcnt(7)
	v_mfma_f32_16x16x32_bf16 v[86:89], v[154:157], v[146:149], v[86:89]
	v_mfma_f32_16x16x32_bf16 v[46:49], v[154:157], v[142:145], v[46:49]
	s_waitcnt lgkmcnt(5)
	v_mfma_f32_16x16x32_bf16 v[82:85], v[162:165], v[146:149], v[82:85]
	v_mfma_f32_16x16x32_bf16 v[38:41], v[162:165], v[142:145], v[38:41]
	s_waitcnt lgkmcnt(3)
	v_mfma_f32_16x16x32_bf16 v[78:81], v[202:205], v[146:149], v[78:81]
	v_mfma_f32_16x16x32_bf16 v[34:37], v[202:205], v[142:145], v[34:37]
	s_waitcnt lgkmcnt(1)
	v_mfma_f32_16x16x32_bf16 v[74:77], v[210:213], v[146:149], v[74:77]
	v_mfma_f32_16x16x32_bf16 v[26:29], v[210:213], v[142:145], v[26:29]
	v_mfma_f32_16x16x32_bf16 v[90:93], v[130:133], v[138:141], v[90:93]
	v_mfma_f32_16x16x32_bf16 v[70:73], v[130:133], v[150:153], v[70:73]
	v_mfma_f32_16x16x32_bf16 v[102:105], v[122:125], v[138:141], v[102:105]
	v_mfma_f32_16x16x32_bf16 v[66:69], v[122:125], v[150:153], v[66:69]
	v_mfma_f32_16x16x32_bf16 v[98:101], v[114:117], v[138:141], v[98:101]
	v_mfma_f32_16x16x32_bf16 v[58:61], v[114:117], v[150:153], v[58:61]
	v_mfma_f32_16x16x32_bf16 v[94:97], v[106:109], v[138:141], v[94:97]
	v_mfma_f32_16x16x32_bf16 v[54:57], v[106:109], v[150:153], v[54:57]
	v_mfma_f32_16x16x32_bf16 v[86:89], v[158:161], v[138:141], v[86:89]
	v_mfma_f32_16x16x32_bf16 v[46:49], v[158:161], v[150:153], v[46:49]
	v_mfma_f32_16x16x32_bf16 v[82:85], v[166:169], v[138:141], v[82:85]
	v_mfma_f32_16x16x32_bf16 v[38:41], v[166:169], v[150:153], v[38:41]
	v_mfma_f32_16x16x32_bf16 v[78:81], v[206:209], v[138:141], v[78:81]
	v_mfma_f32_16x16x32_bf16 v[34:37], v[206:209], v[150:153], v[34:37]
	s_waitcnt lgkmcnt(0)
	v_mfma_f32_16x16x32_bf16 v[74:77], v[216:219], v[138:141], v[74:77]
	v_mfma_f32_16x16x32_bf16 v[26:29], v[216:219], v[150:153], v[26:29]
	s_add_i32 s53, s53, 1
	s_cmp_eq_u32 s53, 3
	s_cselect_b32 s53, 0, s53
	s_add_i32 s49, s49, 64
	s_add_i32 s54, s54, 1
	s_add_u32 s98, s98, 0x4000
	s_addc_u32 s99, s99, 0
	s_add_u32 s2, s2, 0x2000
	s_addc_u32 s3, s3, 0
	s_cmp_lg_u32 s1, s54
	s_cbranch_scc0 .LBB0_42
	v_mov_b32_e32 v200, v199
	v_mov_b32_e32 v198, v201
	s_branch .LBB0_46
